# speedup vs baseline: 1.0012x; 1.0012x over previous
; #define PG8_STAGE(bufoff, gbase, voff) do { _Pragma("unroll") for (int _i = 0; _i < 2; ++_i) \
;         __builtin_amdgcn_global_load_lds((const unsigned*)((const char*)(gbase) + (voff)[_i]), (PG8_LAS unsigned*)(lds + (bufoff) + ldsw + _i * 8192), 16, 0, 0); } while (0)
; #define PG8_LDA(dst, b, h) do { _Pragma("unroll") for (int m = 0; m < 4; ++m) _Pragma("unroll") for (int k = 0; k < 2; ++k) dst[m][k] = *(const PG8_LAS bf16x8*)(lds + PG8_SA(b, h) + aoff + m * 2048 + k * 1024); } while (0)
; #define PG8_LDB(dst, b, h) do { _Pragma("unroll") for (int n = 0; n < 2; ++n) _Pragma("unroll") for (int k = 0; k < 2; ++k) dst[n][k] = *(const PG8_LAS bf16x8*)(lds + PG8_SB(b, h) + boff + n * 2048 + k * 1024); } while (0)
; #define PG8_MMA(ai, bj, At, Bt) do { __builtin_amdgcn_s_setprio(1); _Pragma("unroll") for (int m = 0; m < 4; ++m) _Pragma("unroll") for (int n = 0; n < 2; ++n) _Pragma("unroll") for (int k = 0; k < 2; ++k) \
;         acc[ai][bj][m][n] = __builtin_amdgcn_mfma_f32_16x16x32_bf16(Bt[n][k], At[m][k], acc[ai][bj][m][n], 0, 0, 0); __builtin_amdgcn_s_setprio(0); } while (0)
; #define PG8_WAIT_V(n) asm volatile("s_waitcnt vmcnt(" #n ")" ::: "memory")
; #define PG8_WAIT_L(n) asm volatile("s_waitcnt lgkmcnt(" #n ")" ::: "memory")
; #define PG8_BAR __builtin_amdgcn_s_barrier()
; template <class Epi, class Sched, bool ALIGN_EPI = false, bool SP2 = false>
; __device__ __forceinline__ void gemm_phase(PG8_LAS unsigned char* lds, const Gemm g, const Sched& S, const Epi& E) {
;     ...
;         const bool has_next = S.next(ui + 1, nxt);
;         const char* nA = has_next ? (const char*)g.A + (size_t)nxt.pm * tstep : cA; const char* nB = has_next ? (const char*)g.Bt + (size_t)nxt.pn * tstep : cB;
;         for (int t = 0; t < nt; t += 2) {
;             const bool last = (t == nt - 2);
;             const char* a1 = cA + (size_t)(t + 1) * kstep;
;             const char* a2 = last ? nA : cA + (size_t)(t + 2) * kstep; const char* b2 = last ? nB : cB + (size_t)(t + 2) * kstep;
;             const char* a3 = a2 + kstep; const char* b3 = b2 + kstep;
;             if (last && has_next) S.a_ready(nxt);
;             if constexpr (SP2) {
;             PG8_LDB(B0, 0, 0); PG8_LDB(B1, 0, 1); PG8_SCHED; PG8_LDA(At, 0, 0); PG8_STAGE(PG8_SA(1, 1), a1 + hstep, voffA);
;             PG8_WAIT_V(8); PG8_WAIT_L(0); PG8_BAR; PG8_MMA(0, 0, At, B0); PG8_MMA(0, 1, At, B1); PG8_BAR; PG8_SCHED;
.LBB0_204:
	s_ashr_i32 s61, s60, 31
	s_lshl_b64 s[36:37], s[60:61], 20
	s_add_u32 s62, s45, s36
	s_addc_u32 s63, s44, s37
	s_and_b64 s[36:37], s[6:7], exec
	s_cselect_b32 s9, s63, s69
	s_cselect_b32 s61, s62, s68
	s_ashr_i32 s59, s58, 31
	s_lshl_b64 s[36:37], s[58:59], 20
	s_add_u32 s64, s54, s36
	s_addc_u32 s65, s55, s37
	s_and_b64 s[36:37], s[6:7], exec
	s_cselect_b32 s59, s65, s71
	s_cselect_b32 s87, s64, s70
	s_add_u32 s68, s68, 0x80080
	s_addc_u32 s69, s69, 0
	s_add_u32 s3, s70, 0x100
	s_addc_u32 s88, s71, 0
	s_mov_b32 s89, -2
	s_nop 0
	s_waitcnt vmcnt(16)
	v_add_u32_e32 v204, 0x10000, v238
	s_add_u32 s36, s68, 0xfff80080
	s_addc_u32 s37, s69, -1
	s_add_i32 s38, 0, 0x10000
	s_cmp_eq_u32 s89, 28
	s_cselect_b32 s73, s9, s37
	s_cselect_b32 s72, s61, s36
	s_cselect_b32 s71, s59, s88
	s_cselect_b32 s70, s87, s3
	s_add_i32 s39, 0, 0x14000
	ds_read_b128 v[80:83], v204
	ds_read_b128 v[88:91], v204 offset:1024
	ds_read_b128 v[104:107], v204 offset:2048
	ds_read_b128 v[108:111], v204 offset:3072
	ds_read_b128 v[128:131], v204 offset:16384
	ds_read_b128 v[132:135], v204 offset:17408
	ds_read_b128 v[152:155], v204 offset:18432
	ds_read_b128 v[156:159], v204 offset:19456
	s_add_i32 m0, s67, 0xc000
	ds_read_b128 v[160:163], v240
	ds_read_b128 v[164:167], v240 offset:1024
	ds_read_b128 v[168:171], v240 offset:2048
	ds_read_b128 v[172:175], v240 offset:3072
	ds_read_b128 v[176:179], v240 offset:4096
	ds_read_b128 v[180:183], v240 offset:5120
	ds_read_b128 v[184:187], v240 offset:6144
	ds_read_b128 v[200:203], v240 offset:7168
	global_load_lds_dwordx4 v196, s[68:69]
	s_add_i32 m0, s67, 0xe000
	s_nop 0
	global_load_lds_dwordx4 v198, s[68:69]
	s_waitcnt vmcnt(24)
	s_waitcnt lgkmcnt(0)
	s_barrier
	s_setprio 1
	s_waitcnt lgkmcnt(0)
	v_mfma_f32_16x16x32_bf16 v[148:151], v[80:83], v[160:163], 0
	v_mfma_f32_16x16x32_bf16 v[148:151], v[88:91], v[164:167], v[148:151]
	v_mfma_f32_16x16x32_bf16 v[144:147], v[104:107], v[160:163], 0
	v_mfma_f32_16x16x32_bf16 v[144:147], v[108:111], v[164:167], v[144:147]
	v_mfma_f32_16x16x32_bf16 v[124:127], v[80:83], v[168:171], 0
	v_mfma_f32_16x16x32_bf16 v[124:127], v[88:91], v[172:175], v[124:127]
	v_mfma_f32_16x16x32_bf16 v[120:123], v[104:107], v[168:171], 0
	v_mfma_f32_16x16x32_bf16 v[120:123], v[108:111], v[172:175], v[120:123]
	v_mfma_f32_16x16x32_bf16 v[100:103], v[80:83], v[176:179], 0
	v_mfma_f32_16x16x32_bf16 v[100:103], v[88:91], v[180:183], v[100:103]
	v_mfma_f32_16x16x32_bf16 v[96:99], v[104:107], v[176:179], 0
	v_mfma_f32_16x16x32_bf16 v[96:99], v[108:111], v[180:183], v[96:99]
	v_mfma_f32_16x16x32_bf16 v[76:79], v[80:83], v[184:187], 0
	v_mfma_f32_16x16x32_bf16 v[76:79], v[88:91], v[200:203], v[76:79]
	v_mfma_f32_16x16x32_bf16 v[72:75], v[104:107], v[184:187], 0
	v_mfma_f32_16x16x32_bf16 v[72:75], v[108:111], v[200:203], v[72:75]
	s_setprio 0
	s_setprio 1
	v_mfma_f32_16x16x32_bf16 v[140:143], v[128:131], v[160:163], 0
	v_mfma_f32_16x16x32_bf16 v[140:143], v[132:135], v[164:167], v[140:143]
	v_mfma_f32_16x16x32_bf16 v[136:139], v[152:155], v[160:163], 0
	v_mfma_f32_16x16x32_bf16 v[136:139], v[156:159], v[164:167], v[136:139]
	v_mfma_f32_16x16x32_bf16 v[116:119], v[128:131], v[168:171], 0
	v_mfma_f32_16x16x32_bf16 v[116:119], v[132:135], v[172:175], v[116:119]
	v_mfma_f32_16x16x32_bf16 v[112:115], v[152:155], v[168:171], 0
	v_mfma_f32_16x16x32_bf16 v[112:115], v[156:159], v[172:175], v[112:115]
	v_mfma_f32_16x16x32_bf16 v[92:95], v[128:131], v[176:179], 0
	v_mfma_f32_16x16x32_bf16 v[92:95], v[132:135], v[180:183], v[92:95]
	v_mfma_f32_16x16x32_bf16 v[84:87], v[152:155], v[176:179], 0
	v_mfma_f32_16x16x32_bf16 v[84:87], v[156:159], v[180:183], v[84:87]
	v_mfma_f32_16x16x32_bf16 v[68:71], v[128:131], v[184:187], 0
	v_mfma_f32_16x16x32_bf16 v[68:71], v[132:135], v[200:203], v[68:71]
	v_mfma_f32_16x16x32_bf16 v[64:67], v[152:155], v[184:187], 0
	v_mfma_f32_16x16x32_bf16 v[64:67], v[156:159], v[200:203], v[64:67]
	s_setprio 0
	s_barrier
	s_add_i32 s36, s38, s75
	s_mov_b32 m0, s36
	ds_read_b128 v[160:163], v240 offset:16384
	ds_read_b128 v[164:167], v240 offset:17408
	ds_read_b128 v[168:171], v240 offset:18432
	ds_read_b128 v[172:175], v240 offset:19456
	ds_read_b128 v[176:179], v240 offset:20480
	ds_read_b128 v[180:183], v240 offset:21504
	ds_read_b128 v[184:187], v240 offset:22528
	ds_read_b128 v[200:203], v240 offset:23552
	global_load_lds_dwordx4 v188, s[70:71]
	s_add_i32 m0, s36, 0x2000
	s_add_u32 s36, s70, 0x80000
	s_addc_u32 s37, s71, 0
	s_add_i32 s38, s39, s75
	global_load_lds_dwordx4 v194, s[70:71]
	s_mov_b32 m0, s38
	s_nop 0
	global_load_lds_dwordx4 v188, s[36:37]
	s_add_i32 m0, s38, 0x2000
	s_nop 0
	global_load_lds_dwordx4 v194, s[36:37]
	s_mov_b32 m0, s67
	s_nop 0
	global_load_lds_dwordx4 v188, s[72:73]
	s_mov_b32 m0, s76
	s_nop 0
	global_load_lds_dwordx4 v194, s[72:73]
	s_waitcnt vmcnt(24)
	s_waitcnt lgkmcnt(0)
	s_barrier
; #define PG8_STAGE(bufoff, gbase, voff) do { _Pragma("unroll") for (int _i = 0; _i < 2; ++_i) \
;         __builtin_amdgcn_global_load_lds((const unsigned*)((const char*)(gbase) + (voff)[_i]), (PG8_LAS unsigned*)(lds + (bufoff) + ldsw + _i * 8192), 16, 0, 0); } while (0)
; #define PG8_LDA(dst, b, h) do { _Pragma("unroll") for (int m = 0; m < 4; ++m) _Pragma("unroll") for (int k = 0; k < 2; ++k) dst[m][k] = *(const PG8_LAS bf16x8*)(lds + PG8_SA(b, h) + aoff + m * 2048 + k * 1024); } while (0)
; #define PG8_LDB(dst, b, h) do { _Pragma("unroll") for (int n = 0; n < 2; ++n) _Pragma("unroll") for (int k = 0; k < 2; ++k) dst[n][k] = *(const PG8_LAS bf16x8*)(lds + PG8_SB(b, h) + boff + n * 2048 + k * 1024); } while (0)
; #define PG8_MMA(ai, bj, At, Bt) do { __builtin_amdgcn_s_setprio(1); _Pragma("unroll") for (int m = 0; m < 4; ++m) _Pragma("unroll") for (int n = 0; n < 2; ++n) _Pragma("unroll") for (int k = 0; k < 2; ++k) \
;         acc[ai][bj][m][n] = __builtin_amdgcn_mfma_f32_16x16x32_bf16(Bt[n][k], At[m][k], acc[ai][bj][m][n], 0, 0, 0); __builtin_amdgcn_s_setprio(0); } while (0)
; #define PG8_WAIT_V(n) asm volatile("s_waitcnt vmcnt(" #n ")" ::: "memory")
; #define PG8_WAIT_L(n) asm volatile("s_waitcnt lgkmcnt(" #n ")" ::: "memory")
; #define PG8_BAR __builtin_amdgcn_s_barrier()
; #define PG8_SCHED __builtin_amdgcn_sched_barrier(0)
; template <class Epi, class Sched, bool ALIGN_EPI = false, bool SP2 = false>
; __device__ __forceinline__ void gemm_phase(PG8_LAS unsigned char* lds, const Gemm g, const Sched& S, const Epi& E) {
;     ...
;             PG8_WAIT_V(8); PG8_WAIT_L(0); PG8_BAR; PG8_MMA(0, 0, At, B0); PG8_MMA(0, 1, At, B1); PG8_BAR; PG8_SCHED;
;             PG8_LDA(At, 0, 1); PG8_STAGE(PG8_SB(0, 0), b2, voffB); PG8_STAGE(PG8_SB(0, 1), b2 + hstep, voffB); PG8_STAGE(PG8_SA(0, 0), a2, voffA);
;             PG8_WAIT_V(8); PG8_WAIT_L(0); PG8_BAR; PG8_MMA(1, 0, At, B0); PG8_MMA(1, 1, At, B1); PG8_BAR; PG8_SCHED;
;             PG8_LDB(B0, 1, 0); PG8_LDB(B1, 1, 1); PG8_SCHED; PG8_LDA(At, 1, 0); PG8_STAGE(PG8_SA(0, 1), a2 + hstep, voffA);
;             PG8_WAIT_V(8); PG8_WAIT_L(0); PG8_BAR; PG8_MMA(0, 0, At, B0); PG8_MMA(0, 1, At, B1); PG8_BAR; PG8_SCHED;
	s_setprio 1
	s_waitcnt lgkmcnt(0)
	v_mfma_f32_16x16x32_bf16 v[60:63], v[80:83], v[160:163], 0
	v_mfma_f32_16x16x32_bf16 v[60:63], v[88:91], v[164:167], v[60:63]
	v_mfma_f32_16x16x32_bf16 v[56:59], v[104:107], v[160:163], 0
	v_mfma_f32_16x16x32_bf16 v[56:59], v[108:111], v[164:167], v[56:59]
	v_mfma_f32_16x16x32_bf16 v[44:47], v[80:83], v[168:171], 0
	v_mfma_f32_16x16x32_bf16 v[44:47], v[88:91], v[172:175], v[44:47]
	v_mfma_f32_16x16x32_bf16 v[40:43], v[104:107], v[168:171], 0
	v_mfma_f32_16x16x32_bf16 v[40:43], v[108:111], v[172:175], v[40:43]
	v_mfma_f32_16x16x32_bf16 v[28:31], v[80:83], v[176:179], 0
	v_mfma_f32_16x16x32_bf16 v[28:31], v[88:91], v[180:183], v[28:31]
	v_mfma_f32_16x16x32_bf16 v[24:27], v[104:107], v[176:179], 0
	v_mfma_f32_16x16x32_bf16 v[24:27], v[108:111], v[180:183], v[24:27]
	v_mfma_f32_16x16x32_bf16 v[12:15], v[80:83], v[184:187], 0
	v_mfma_f32_16x16x32_bf16 v[12:15], v[88:91], v[200:203], v[12:15]
	v_mfma_f32_16x16x32_bf16 v[8:11], v[104:107], v[184:187], 0
	v_mfma_f32_16x16x32_bf16 v[8:11], v[108:111], v[200:203], v[8:11]
	s_setprio 0
	s_setprio 1
	v_mfma_f32_16x16x32_bf16 v[52:55], v[128:131], v[160:163], 0
	v_mfma_f32_16x16x32_bf16 v[52:55], v[132:135], v[164:167], v[52:55]
	v_mfma_f32_16x16x32_bf16 v[48:51], v[152:155], v[160:163], 0
	v_mfma_f32_16x16x32_bf16 v[48:51], v[156:159], v[164:167], v[48:51]
	v_mfma_f32_16x16x32_bf16 v[36:39], v[128:131], v[168:171], 0
	v_mfma_f32_16x16x32_bf16 v[36:39], v[132:135], v[172:175], v[36:39]
	v_mfma_f32_16x16x32_bf16 v[32:35], v[152:155], v[168:171], 0
	v_mfma_f32_16x16x32_bf16 v[32:35], v[156:159], v[172:175], v[32:35]
	v_mfma_f32_16x16x32_bf16 v[20:23], v[128:131], v[176:179], 0
	v_mfma_f32_16x16x32_bf16 v[20:23], v[132:135], v[180:183], v[20:23]
	v_mfma_f32_16x16x32_bf16 v[16:19], v[152:155], v[176:179], 0
	v_mfma_f32_16x16x32_bf16 v[16:19], v[156:159], v[180:183], v[16:19]
	v_mfma_f32_16x16x32_bf16 v[4:7], v[128:131], v[184:187], 0
	v_mfma_f32_16x16x32_bf16 v[4:7], v[132:135], v[200:203], v[4:7]
	v_mfma_f32_16x16x32_bf16 v[0:3], v[152:155], v[184:187], 0
	v_mfma_f32_16x16x32_bf16 v[0:3], v[156:159], v[200:203], v[0:3]
	s_setprio 0
	s_barrier
	s_add_i32 s38, 0, 0x18000
	s_add_i32 s39, 0, 0x1c000
	ds_read_b128 v[80:83], v204 offset:32768
	ds_read_b128 v[88:91], v204 offset:33792
	ds_read_b128 v[104:107], v204 offset:34816
	ds_read_b128 v[108:111], v204 offset:35840
	ds_read_b128 v[128:131], v204 offset:49152
	ds_read_b128 v[132:135], v204 offset:50176
	ds_read_b128 v[152:155], v204 offset:51200
	ds_read_b128 v[156:159], v204 offset:52224
	s_add_u32 s36, s72, 0x80000
	s_addc_u32 s37, s73, 0
	s_mov_b32 m0, s77
	ds_read_b128 v[160:163], v240 offset:32768
	ds_read_b128 v[164:167], v240 offset:33792
	ds_read_b128 v[168:171], v240 offset:34816
	ds_read_b128 v[172:175], v240 offset:35840
	ds_read_b128 v[176:179], v240 offset:36864
	ds_read_b128 v[180:183], v240 offset:37888
	ds_read_b128 v[184:187], v240 offset:38912
	ds_read_b128 v[200:203], v240 offset:39936
	global_load_lds_dwordx4 v188, s[36:37]
	s_mov_b32 m0, s78
	s_nop 0
	global_load_lds_dwordx4 v194, s[36:37]
	s_waitcnt vmcnt(8)
	s_waitcnt lgkmcnt(0)
	s_barrier
	s_setprio 1
	s_waitcnt lgkmcnt(0)
	v_mfma_f32_16x16x32_bf16 v[148:151], v[80:83], v[160:163], v[148:151]
	v_mfma_f32_16x16x32_bf16 v[148:151], v[88:91], v[164:167], v[148:151]
	v_mfma_f32_16x16x32_bf16 v[144:147], v[104:107], v[160:163], v[144:147]
	v_mfma_f32_16x16x32_bf16 v[144:147], v[108:111], v[164:167], v[144:147]
	v_mfma_f32_16x16x32_bf16 v[124:127], v[80:83], v[168:171], v[124:127]
	v_mfma_f32_16x16x32_bf16 v[124:127], v[88:91], v[172:175], v[124:127]
	v_mfma_f32_16x16x32_bf16 v[120:123], v[104:107], v[168:171], v[120:123]
	v_mfma_f32_16x16x32_bf16 v[120:123], v[108:111], v[172:175], v[120:123]
	v_mfma_f32_16x16x32_bf16 v[100:103], v[80:83], v[176:179], v[100:103]
	v_mfma_f32_16x16x32_bf16 v[100:103], v[88:91], v[180:183], v[100:103]
	v_mfma_f32_16x16x32_bf16 v[96:99], v[104:107], v[176:179], v[96:99]
	v_mfma_f32_16x16x32_bf16 v[96:99], v[108:111], v[180:183], v[96:99]
	v_mfma_f32_16x16x32_bf16 v[76:79], v[80:83], v[184:187], v[76:79]
	v_mfma_f32_16x16x32_bf16 v[76:79], v[88:91], v[200:203], v[76:79]
	v_mfma_f32_16x16x32_bf16 v[72:75], v[104:107], v[184:187], v[72:75]
	v_mfma_f32_16x16x32_bf16 v[72:75], v[108:111], v[200:203], v[72:75]
	s_setprio 0
	s_setprio 1
	v_mfma_f32_16x16x32_bf16 v[140:143], v[128:131], v[160:163], v[140:143]
	v_mfma_f32_16x16x32_bf16 v[140:143], v[132:135], v[164:167], v[140:143]
	v_mfma_f32_16x16x32_bf16 v[136:139], v[152:155], v[160:163], v[136:139]
	v_mfma_f32_16x16x32_bf16 v[136:139], v[156:159], v[164:167], v[136:139]
	v_mfma_f32_16x16x32_bf16 v[116:119], v[128:131], v[168:171], v[116:119]
	v_mfma_f32_16x16x32_bf16 v[116:119], v[132:135], v[172:175], v[116:119]
	v_mfma_f32_16x16x32_bf16 v[112:115], v[152:155], v[168:171], v[112:115]
	v_mfma_f32_16x16x32_bf16 v[112:115], v[156:159], v[172:175], v[112:115]
	v_mfma_f32_16x16x32_bf16 v[92:95], v[128:131], v[176:179], v[92:95]
	v_mfma_f32_16x16x32_bf16 v[92:95], v[132:135], v[180:183], v[92:95]
	v_mfma_f32_16x16x32_bf16 v[84:87], v[152:155], v[176:179], v[84:87]
	v_mfma_f32_16x16x32_bf16 v[84:87], v[156:159], v[180:183], v[84:87]
	v_mfma_f32_16x16x32_bf16 v[68:71], v[128:131], v[184:187], v[68:71]
	v_mfma_f32_16x16x32_bf16 v[68:71], v[132:135], v[200:203], v[68:71]
	v_mfma_f32_16x16x32_bf16 v[64:67], v[152:155], v[184:187], v[64:67]
	v_mfma_f32_16x16x32_bf16 v[64:67], v[156:159], v[200:203], v[64:67]
	s_setprio 0
	s_barrier
; #define PG8_STAGE(bufoff, gbase, voff) do { _Pragma("unroll") for (int _i = 0; _i < 2; ++_i) \
;         __builtin_amdgcn_global_load_lds((const unsigned*)((const char*)(gbase) + (voff)[_i]), (PG8_LAS unsigned*)(lds + (bufoff) + ldsw + _i * 8192), 16, 0, 0); } while (0)
; #define PG8_LDA(dst, b, h) do { _Pragma("unroll") for (int m = 0; m < 4; ++m) _Pragma("unroll") for (int k = 0; k < 2; ++k) dst[m][k] = *(const PG8_LAS bf16x8*)(lds + PG8_SA(b, h) + aoff + m * 2048 + k * 1024); } while (0)
; #define PG8_MMA(ai, bj, At, Bt) do { __builtin_amdgcn_s_setprio(1); _Pragma("unroll") for (int m = 0; m < 4; ++m) _Pragma("unroll") for (int n = 0; n < 2; ++n) _Pragma("unroll") for (int k = 0; k < 2; ++k) \
;         acc[ai][bj][m][n] = __builtin_amdgcn_mfma_f32_16x16x32_bf16(Bt[n][k], At[m][k], acc[ai][bj][m][n], 0, 0, 0); __builtin_amdgcn_s_setprio(0); } while (0)
; #define PG8_WAIT_V(n) asm volatile("s_waitcnt vmcnt(" #n ")" ::: "memory")
; #define PG8_WAIT_L(n) asm volatile("s_waitcnt lgkmcnt(" #n ")" ::: "memory")
; #define PG8_BAR __builtin_amdgcn_s_barrier()
; #define PG8_SCHED __builtin_amdgcn_sched_barrier(0)
; template <class Epi, class Sched, bool ALIGN_EPI = false, bool SP2 = false>
; __device__ __forceinline__ void gemm_phase(PG8_LAS unsigned char* lds, const Gemm g, const Sched& S, const Epi& E) {
;     ...
;         for (int t = 0; t < nt; t += 2) {
;     ...
;             PG8_LDA(At, 1, 1); PG8_STAGE(PG8_SB(1, 0), b3, voffB); PG8_STAGE(PG8_SB(1, 1), b3 + hstep, voffB); PG8_STAGE(PG8_SA(1, 0), a3, voffA);
;             PG8_WAIT_V(8); PG8_WAIT_L(0); PG8_BAR; PG8_MMA(1, 0, At, B0); PG8_MMA(1, 1, At, B1); PG8_BAR; PG8_SCHED;
	s_add_i32 s36, s38, s75
	s_mov_b32 m0, s36
	ds_read_b128 v[160:163], v240 offset:49152
	ds_read_b128 v[164:167], v240 offset:50176
	ds_read_b128 v[168:171], v240 offset:51200
	ds_read_b128 v[172:175], v240 offset:52224
	ds_read_b128 v[176:179], v240 offset:53248
	ds_read_b128 v[180:183], v240 offset:54272
	ds_read_b128 v[184:187], v240 offset:55296
	ds_read_b128 v[200:203], v240 offset:56320
	s_add_u32 s100, s70, 0x80
	s_addc_u32 s101, s71, 0
	global_load_lds_dwordx4 v188, s[100:101]
	s_add_i32 m0, s36, 0x2000
	s_add_u32 s36, s70, 0x80080
	s_addc_u32 s37, s71, 0
	s_add_i32 s38, s39, s75
	global_load_lds_dwordx4 v194, s[100:101]
	s_mov_b32 m0, s38
	s_nop 0
	global_load_lds_dwordx4 v188, s[36:37]
	s_add_i32 m0, s38, 0x2000
	s_nop 0
	global_load_lds_dwordx4 v194, s[36:37]
	s_mov_b32 m0, s79
	s_nop 0
	s_add_u32 s100, s72, 0x80
	s_addc_u32 s101, s73, 0
	global_load_lds_dwordx4 v188, s[100:101]
	s_mov_b32 m0, s80
	s_nop 0
	global_load_lds_dwordx4 v194, s[100:101]
	s_waitcnt vmcnt(8)
	s_waitcnt lgkmcnt(0)
	s_barrier
	s_setprio 1
	s_waitcnt lgkmcnt(0)
	v_mfma_f32_16x16x32_bf16 v[60:63], v[80:83], v[160:163], v[60:63]
	v_mfma_f32_16x16x32_bf16 v[60:63], v[88:91], v[164:167], v[60:63]
	v_mfma_f32_16x16x32_bf16 v[56:59], v[104:107], v[160:163], v[56:59]
	v_mfma_f32_16x16x32_bf16 v[56:59], v[108:111], v[164:167], v[56:59]
	v_mfma_f32_16x16x32_bf16 v[44:47], v[80:83], v[168:171], v[44:47]
	v_mfma_f32_16x16x32_bf16 v[44:47], v[88:91], v[172:175], v[44:47]
	v_mfma_f32_16x16x32_bf16 v[40:43], v[104:107], v[168:171], v[40:43]
	v_mfma_f32_16x16x32_bf16 v[40:43], v[108:111], v[172:175], v[40:43]
	v_mfma_f32_16x16x32_bf16 v[28:31], v[80:83], v[176:179], v[28:31]
	v_mfma_f32_16x16x32_bf16 v[28:31], v[88:91], v[180:183], v[28:31]
	v_mfma_f32_16x16x32_bf16 v[24:27], v[104:107], v[176:179], v[24:27]
	v_mfma_f32_16x16x32_bf16 v[24:27], v[108:111], v[180:183], v[24:27]
	v_mfma_f32_16x16x32_bf16 v[12:15], v[80:83], v[184:187], v[12:15]
	v_mfma_f32_16x16x32_bf16 v[12:15], v[88:91], v[200:203], v[12:15]
	v_mfma_f32_16x16x32_bf16 v[8:11], v[104:107], v[184:187], v[8:11]
	v_mfma_f32_16x16x32_bf16 v[8:11], v[108:111], v[200:203], v[8:11]
	s_setprio 0
	s_setprio 1
	v_mfma_f32_16x16x32_bf16 v[52:55], v[128:131], v[160:163], v[52:55]
	v_mfma_f32_16x16x32_bf16 v[52:55], v[132:135], v[164:167], v[52:55]
	v_mfma_f32_16x16x32_bf16 v[48:51], v[152:155], v[160:163], v[48:51]
	v_mfma_f32_16x16x32_bf16 v[48:51], v[156:159], v[164:167], v[48:51]
	v_mfma_f32_16x16x32_bf16 v[36:39], v[128:131], v[168:171], v[36:39]
	v_mfma_f32_16x16x32_bf16 v[36:39], v[132:135], v[172:175], v[36:39]
	v_mfma_f32_16x16x32_bf16 v[32:35], v[152:155], v[168:171], v[32:35]
	v_mfma_f32_16x16x32_bf16 v[32:35], v[156:159], v[172:175], v[32:35]
	v_mfma_f32_16x16x32_bf16 v[20:23], v[128:131], v[176:179], v[20:23]
	v_mfma_f32_16x16x32_bf16 v[20:23], v[132:135], v[180:183], v[20:23]
	v_mfma_f32_16x16x32_bf16 v[16:19], v[152:155], v[176:179], v[16:19]
	v_mfma_f32_16x16x32_bf16 v[16:19], v[156:159], v[180:183], v[16:19]
	v_mfma_f32_16x16x32_bf16 v[4:7], v[128:131], v[184:187], v[4:7]
	v_mfma_f32_16x16x32_bf16 v[4:7], v[132:135], v[200:203], v[4:7]
	v_mfma_f32_16x16x32_bf16 v[0:3], v[152:155], v[184:187], v[0:3]
	v_mfma_f32_16x16x32_bf16 v[0:3], v[156:159], v[200:203], v[0:3]
	s_setprio 0
	s_barrier
	s_add_i32 s89, s89, 2
	s_add_u32 s68, s68, 0x100
	s_addc_u32 s69, s69, 0
	s_add_u32 s3, s3, 0x100
	s_addc_u32 s88, s88, 0
	s_cmp_gt_u32 s89, 29

; #define PG8_STAGE(bufoff, gbase, voff) do { _Pragma("unroll") for (int _i = 0; _i < 2; ++_i) \
;         __builtin_amdgcn_global_load_lds((const unsigned*)((const char*)(gbase) + (voff)[_i]), (PG8_LAS unsigned*)(lds + (bufoff) + ldsw + _i * 8192), 16, 0, 0); } while (0)
; #define PG8_LDA(dst, b, h) do { _Pragma("unroll") for (int m = 0; m < 4; ++m) _Pragma("unroll") for (int k = 0; k < 2; ++k) dst[m][k] = *(const PG8_LAS bf16x8*)(lds + PG8_SA(b, h) + aoff + m * 2048 + k * 1024); } while (0)
; #define PG8_LDB(dst, b, h) do { _Pragma("unroll") for (int n = 0; n < 2; ++n) _Pragma("unroll") for (int k = 0; k < 2; ++k) dst[n][k] = *(const PG8_LAS bf16x8*)(lds + PG8_SB(b, h) + boff + n * 2048 + k * 1024); } while (0)
; #define PG8_MMA(ai, bj, At, Bt) do { __builtin_amdgcn_s_setprio(1); _Pragma("unroll") for (int m = 0; m < 4; ++m) _Pragma("unroll") for (int n = 0; n < 2; ++n) _Pragma("unroll") for (int k = 0; k < 2; ++k) \
;         acc[ai][bj][m][n] = __builtin_amdgcn_mfma_f32_16x16x32_bf16(Bt[n][k], At[m][k], acc[ai][bj][m][n], 0, 0, 0); __builtin_amdgcn_s_setprio(0); } while (0)
; #define PG8_WAIT_V(n) asm volatile("s_waitcnt vmcnt(" #n ")" ::: "memory")
; #define PG8_WAIT_L(n) asm volatile("s_waitcnt lgkmcnt(" #n ")" ::: "memory")
; #define PG8_BAR __builtin_amdgcn_s_barrier()
; template <class Epi, class Sched, bool ALIGN_EPI = false, bool SP2 = false>
; __device__ __forceinline__ void gemm_phase(PG8_LAS unsigned char* lds, const Gemm g, const Sched& S, const Epi& E) {
;     ...
;         const bool has_next = S.next(ui + 1, nxt);
;         const char* nA = has_next ? (const char*)g.A + (size_t)nxt.pm * tstep : cA; const char* nB = has_next ? (const char*)g.Bt + (size_t)nxt.pn * tstep : cB;
;         for (int t = 0; t < nt; t += 2) {
;             const bool last = (t == nt - 2);
;             const char* a1 = cA + (size_t)(t + 1) * kstep;
;             const char* a2 = last ? nA : cA + (size_t)(t + 2) * kstep; const char* b2 = last ? nB : cB + (size_t)(t + 2) * kstep;
;             const char* a3 = a2 + kstep; const char* b3 = b2 + kstep;
;             if (last && has_next) S.a_ready(nxt);
;             if constexpr (SP2) {
;             PG8_LDB(B0, 0, 0); PG8_LDB(B1, 0, 1); PG8_SCHED; PG8_LDA(At, 0, 0); PG8_STAGE(PG8_SA(1, 1), a1 + hstep, voffA);
;             PG8_WAIT_V(8); PG8_WAIT_L(0); PG8_BAR; PG8_MMA(0, 0, At, B0); PG8_MMA(0, 1, At, B1); PG8_BAR; PG8_SCHED;
.LBB0_297:
	s_ashr_i32 s67, s66, 31
	s_lshl_b64 s[76:77], s[66:67], 20
	s_add_u32 s78, s34, s76
	s_addc_u32 s79, s35, s77
	s_and_b64 s[76:77], s[12:13], exec
	s_cselect_b32 s65, s79, s69
	s_cselect_b32 s67, s78, s68
	s_ashr_i32 s75, s74, 31
	s_lshl_b64 s[76:77], s[74:75], 20
	s_add_u32 s76, s0, s76
	s_addc_u32 s77, s1, s77
	s_and_b64 s[94:95], s[12:13], exec
	s_cselect_b32 s73, s77, s71
	s_cselect_b32 s75, s76, s70
	s_add_u32 vcc_lo, s68, 0x80080
	s_addc_u32 vcc_hi, s69, 0
	s_add_u32 s3, s70, 0x100
	s_addc_u32 s94, s71, 0
	s_mov_b32 s95, -2
	s_waitcnt vmcnt(8)
	v_add_u32_e32 v214, 0x10000, v165
	s_add_u32 s36, vcc_lo, 0xfff80080
	s_addc_u32 s37, vcc_hi, -1
	s_add_i32 s38, 0, 0x10000
	s_cmp_eq_u32 s95, 28
	s_cselect_b32 s71, s65, s37
	s_cselect_b32 s70, s67, s36
	s_cselect_b32 s69, s73, s94
	s_cselect_b32 s68, s75, s3
	s_add_i32 s39, 0, 0x14000
	ds_read_b128 v[64:67], v214
	ds_read_b128 v[68:71], v214 offset:1024
	ds_read_b128 v[72:75], v214 offset:2048
	ds_read_b128 v[146:149], v214 offset:3072
	ds_read_b128 v[150:153], v214 offset:16384
	ds_read_b128 v[154:157], v214 offset:17408
	ds_read_b128 v[158:161], v214 offset:18432
	ds_read_b128 v[170:173], v214 offset:19456
	s_add_i32 m0, s88, 0xc000
	ds_read_b128 v[174:177], v169
	ds_read_b128 v[178:181], v169 offset:1024
	ds_read_b128 v[182:185], v169 offset:2048
	ds_read_b128 v[194:197], v169 offset:3072
	ds_read_b128 v[198:201], v169 offset:4096
	ds_read_b128 v[202:205], v169 offset:5120
	ds_read_b128 v[206:209], v169 offset:6144
	ds_read_b128 v[210:213], v169 offset:7168
	global_load_lds_dwordx4 v142, vcc
	s_add_i32 m0, s88, 0xe000
	s_nop 0
	global_load_lds_dwordx4 v144, vcc
	s_waitcnt vmcnt(24)
	s_waitcnt lgkmcnt(0)
	s_barrier
	s_setprio 1
	s_waitcnt lgkmcnt(0)
	v_mfma_f32_16x16x32_bf16 v[136:139], v[64:67], v[174:177], 0
	v_mfma_f32_16x16x32_bf16 v[136:139], v[68:71], v[178:181], v[136:139]
	v_mfma_f32_16x16x32_bf16 v[132:135], v[72:75], v[174:177], 0
	v_mfma_f32_16x16x32_bf16 v[132:135], v[146:149], v[178:181], v[132:135]
	v_mfma_f32_16x16x32_bf16 v[120:123], v[64:67], v[182:185], 0
	v_mfma_f32_16x16x32_bf16 v[120:123], v[68:71], v[194:197], v[120:123]
	v_mfma_f32_16x16x32_bf16 v[116:119], v[72:75], v[182:185], 0
	v_mfma_f32_16x16x32_bf16 v[116:119], v[146:149], v[194:197], v[116:119]
	v_mfma_f32_16x16x32_bf16 v[104:107], v[64:67], v[198:201], 0
	v_mfma_f32_16x16x32_bf16 v[104:107], v[68:71], v[202:205], v[104:107]
	v_mfma_f32_16x16x32_bf16 v[100:103], v[72:75], v[198:201], 0
	v_mfma_f32_16x16x32_bf16 v[100:103], v[146:149], v[202:205], v[100:103]
	v_mfma_f32_16x16x32_bf16 v[88:91], v[64:67], v[206:209], 0
	v_mfma_f32_16x16x32_bf16 v[88:91], v[68:71], v[210:213], v[88:91]
	v_mfma_f32_16x16x32_bf16 v[84:87], v[72:75], v[206:209], 0
	v_mfma_f32_16x16x32_bf16 v[84:87], v[146:149], v[210:213], v[84:87]
	s_setprio 0
	s_setprio 1
	v_mfma_f32_16x16x32_bf16 v[128:131], v[150:153], v[174:177], 0
	v_mfma_f32_16x16x32_bf16 v[128:131], v[154:157], v[178:181], v[128:131]
	v_mfma_f32_16x16x32_bf16 v[124:127], v[158:161], v[174:177], 0
	v_mfma_f32_16x16x32_bf16 v[124:127], v[170:173], v[178:181], v[124:127]
	v_mfma_f32_16x16x32_bf16 v[112:115], v[150:153], v[182:185], 0
	v_mfma_f32_16x16x32_bf16 v[112:115], v[154:157], v[194:197], v[112:115]
	v_mfma_f32_16x16x32_bf16 v[108:111], v[158:161], v[182:185], 0
	v_mfma_f32_16x16x32_bf16 v[108:111], v[170:173], v[194:197], v[108:111]
	v_mfma_f32_16x16x32_bf16 v[96:99], v[150:153], v[198:201], 0
	v_mfma_f32_16x16x32_bf16 v[96:99], v[154:157], v[202:205], v[96:99]
	v_mfma_f32_16x16x32_bf16 v[92:95], v[158:161], v[198:201], 0
	v_mfma_f32_16x16x32_bf16 v[92:95], v[170:173], v[202:205], v[92:95]
	v_mfma_f32_16x16x32_bf16 v[80:83], v[150:153], v[206:209], 0
	v_mfma_f32_16x16x32_bf16 v[80:83], v[154:157], v[210:213], v[80:83]
	v_mfma_f32_16x16x32_bf16 v[76:79], v[158:161], v[206:209], 0
	v_mfma_f32_16x16x32_bf16 v[76:79], v[170:173], v[210:213], v[76:79]
	s_setprio 0
	s_barrier
	s_add_i32 s36, s38, s87
	s_mov_b32 m0, s36
	ds_read_b128 v[174:177], v169 offset:16384
	ds_read_b128 v[178:181], v169 offset:17408
	ds_read_b128 v[182:185], v169 offset:18432
	ds_read_b128 v[194:197], v169 offset:19456
	ds_read_b128 v[198:201], v169 offset:20480
	ds_read_b128 v[202:205], v169 offset:21504
	ds_read_b128 v[206:209], v169 offset:22528
	ds_read_b128 v[210:213], v169 offset:23552
	global_load_lds_dwordx4 v188, s[68:69]
	s_add_i32 m0, s36, 0x2000
	s_add_u32 s36, s68, 0x80000
	s_addc_u32 s37, s69, 0
	s_add_i32 s38, s39, s87
	global_load_lds_dwordx4 v140, s[68:69]
	s_mov_b32 m0, s38
	s_nop 0
	global_load_lds_dwordx4 v188, s[36:37]
	s_add_i32 m0, s38, 0x2000
	s_nop 0
	global_load_lds_dwordx4 v140, s[36:37]
	s_mov_b32 m0, s88
	s_nop 0
	global_load_lds_dwordx4 v188, s[70:71]
	s_mov_b32 m0, s89
	s_nop 0
	global_load_lds_dwordx4 v140, s[70:71]
	s_waitcnt vmcnt(24)
	s_waitcnt lgkmcnt(0)
	s_barrier
; #define PG8_STAGE(bufoff, gbase, voff) do { _Pragma("unroll") for (int _i = 0; _i < 2; ++_i) \
;         __builtin_amdgcn_global_load_lds((const unsigned*)((const char*)(gbase) + (voff)[_i]), (PG8_LAS unsigned*)(lds + (bufoff) + ldsw + _i * 8192), 16, 0, 0); } while (0)
; #define PG8_LDA(dst, b, h) do { _Pragma("unroll") for (int m = 0; m < 4; ++m) _Pragma("unroll") for (int k = 0; k < 2; ++k) dst[m][k] = *(const PG8_LAS bf16x8*)(lds + PG8_SA(b, h) + aoff + m * 2048 + k * 1024); } while (0)
; #define PG8_LDB(dst, b, h) do { _Pragma("unroll") for (int n = 0; n < 2; ++n) _Pragma("unroll") for (int k = 0; k < 2; ++k) dst[n][k] = *(const PG8_LAS bf16x8*)(lds + PG8_SB(b, h) + boff + n * 2048 + k * 1024); } while (0)
; #define PG8_MMA(ai, bj, At, Bt) do { __builtin_amdgcn_s_setprio(1); _Pragma("unroll") for (int m = 0; m < 4; ++m) _Pragma("unroll") for (int n = 0; n < 2; ++n) _Pragma("unroll") for (int k = 0; k < 2; ++k) \
;         acc[ai][bj][m][n] = __builtin_amdgcn_mfma_f32_16x16x32_bf16(Bt[n][k], At[m][k], acc[ai][bj][m][n], 0, 0, 0); __builtin_amdgcn_s_setprio(0); } while (0)
; #define PG8_WAIT_V(n) asm volatile("s_waitcnt vmcnt(" #n ")" ::: "memory")
; #define PG8_WAIT_L(n) asm volatile("s_waitcnt lgkmcnt(" #n ")" ::: "memory")
; #define PG8_BAR __builtin_amdgcn_s_barrier()
; #define PG8_SCHED __builtin_amdgcn_sched_barrier(0)
; template <class Epi, class Sched, bool ALIGN_EPI = false, bool SP2 = false>
; __device__ __forceinline__ void gemm_phase(PG8_LAS unsigned char* lds, const Gemm g, const Sched& S, const Epi& E) {
;     ...
;             PG8_WAIT_V(8); PG8_WAIT_L(0); PG8_BAR; PG8_MMA(0, 0, At, B0); PG8_MMA(0, 1, At, B1); PG8_BAR; PG8_SCHED;
;             PG8_LDA(At, 0, 1); PG8_STAGE(PG8_SB(0, 0), b2, voffB); PG8_STAGE(PG8_SB(0, 1), b2 + hstep, voffB); PG8_STAGE(PG8_SA(0, 0), a2, voffA);
;             PG8_WAIT_V(8); PG8_WAIT_L(0); PG8_BAR; PG8_MMA(1, 0, At, B0); PG8_MMA(1, 1, At, B1); PG8_BAR; PG8_SCHED;
;             PG8_LDB(B0, 1, 0); PG8_LDB(B1, 1, 1); PG8_SCHED; PG8_LDA(At, 1, 0); PG8_STAGE(PG8_SA(0, 1), a2 + hstep, voffA);
;             PG8_WAIT_V(8); PG8_WAIT_L(0); PG8_BAR; PG8_MMA(0, 0, At, B0); PG8_MMA(0, 1, At, B1); PG8_BAR; PG8_SCHED;
	s_setprio 1
	s_waitcnt lgkmcnt(0)
	v_mfma_f32_16x16x32_bf16 v[56:59], v[64:67], v[174:177], 0
	v_mfma_f32_16x16x32_bf16 v[56:59], v[68:71], v[178:181], v[56:59]
	v_mfma_f32_16x16x32_bf16 v[60:63], v[72:75], v[174:177], 0
	v_mfma_f32_16x16x32_bf16 v[60:63], v[146:149], v[178:181], v[60:63]
	v_mfma_f32_16x16x32_bf16 v[40:43], v[64:67], v[182:185], 0
	v_mfma_f32_16x16x32_bf16 v[40:43], v[68:71], v[194:197], v[40:43]
	v_mfma_f32_16x16x32_bf16 v[44:47], v[72:75], v[182:185], 0
	v_mfma_f32_16x16x32_bf16 v[44:47], v[146:149], v[194:197], v[44:47]
	v_mfma_f32_16x16x32_bf16 v[24:27], v[64:67], v[198:201], 0
	v_mfma_f32_16x16x32_bf16 v[24:27], v[68:71], v[202:205], v[24:27]
	v_mfma_f32_16x16x32_bf16 v[28:31], v[72:75], v[198:201], 0
	v_mfma_f32_16x16x32_bf16 v[28:31], v[146:149], v[202:205], v[28:31]
	v_mfma_f32_16x16x32_bf16 v[8:11], v[64:67], v[206:209], 0
	v_mfma_f32_16x16x32_bf16 v[8:11], v[68:71], v[210:213], v[8:11]
	v_mfma_f32_16x16x32_bf16 v[12:15], v[72:75], v[206:209], 0
	v_mfma_f32_16x16x32_bf16 v[12:15], v[146:149], v[210:213], v[12:15]
	s_setprio 0
	s_setprio 1
	v_mfma_f32_16x16x32_bf16 v[52:55], v[150:153], v[174:177], 0
	v_mfma_f32_16x16x32_bf16 v[52:55], v[154:157], v[178:181], v[52:55]
	v_mfma_f32_16x16x32_bf16 v[48:51], v[158:161], v[174:177], 0
	v_mfma_f32_16x16x32_bf16 v[48:51], v[170:173], v[178:181], v[48:51]
	v_mfma_f32_16x16x32_bf16 v[36:39], v[150:153], v[182:185], 0
	v_mfma_f32_16x16x32_bf16 v[36:39], v[154:157], v[194:197], v[36:39]
	v_mfma_f32_16x16x32_bf16 v[32:35], v[158:161], v[182:185], 0
	v_mfma_f32_16x16x32_bf16 v[32:35], v[170:173], v[194:197], v[32:35]
	v_mfma_f32_16x16x32_bf16 v[20:23], v[150:153], v[198:201], 0
	v_mfma_f32_16x16x32_bf16 v[20:23], v[154:157], v[202:205], v[20:23]
	v_mfma_f32_16x16x32_bf16 v[16:19], v[158:161], v[198:201], 0
	v_mfma_f32_16x16x32_bf16 v[16:19], v[170:173], v[202:205], v[16:19]
	v_mfma_f32_16x16x32_bf16 v[4:7], v[150:153], v[206:209], 0
	v_mfma_f32_16x16x32_bf16 v[4:7], v[154:157], v[210:213], v[4:7]
	v_mfma_f32_16x16x32_bf16 v[0:3], v[158:161], v[206:209], 0
	v_mfma_f32_16x16x32_bf16 v[0:3], v[170:173], v[210:213], v[0:3]
	s_setprio 0
	s_barrier
	s_add_i32 s38, 0, 0x18000
	s_add_i32 s39, 0, 0x1c000
	ds_read_b128 v[64:67], v214 offset:32768
	ds_read_b128 v[68:71], v214 offset:33792
	ds_read_b128 v[72:75], v214 offset:34816
	ds_read_b128 v[146:149], v214 offset:35840
	ds_read_b128 v[150:153], v214 offset:49152
	ds_read_b128 v[154:157], v214 offset:50176
	ds_read_b128 v[158:161], v214 offset:51200
	ds_read_b128 v[170:173], v214 offset:52224
	s_add_u32 s36, s70, 0x80000
	s_addc_u32 s37, s71, 0
	s_mov_b32 m0, s14
	ds_read_b128 v[174:177], v169 offset:32768
	ds_read_b128 v[178:181], v169 offset:33792
	ds_read_b128 v[182:185], v169 offset:34816
	ds_read_b128 v[194:197], v169 offset:35840
	ds_read_b128 v[198:201], v169 offset:36864
	ds_read_b128 v[202:205], v169 offset:37888
	ds_read_b128 v[206:209], v169 offset:38912
	ds_read_b128 v[210:213], v169 offset:39936
	global_load_lds_dwordx4 v188, s[36:37]
	s_mov_b32 m0, s15
	s_nop 0
	global_load_lds_dwordx4 v140, s[36:37]
	s_waitcnt vmcnt(8)
	s_waitcnt lgkmcnt(0)
	s_barrier
	s_setprio 1
	s_waitcnt lgkmcnt(0)
	v_mfma_f32_16x16x32_bf16 v[136:139], v[64:67], v[174:177], v[136:139]
	v_mfma_f32_16x16x32_bf16 v[136:139], v[68:71], v[178:181], v[136:139]
	v_mfma_f32_16x16x32_bf16 v[132:135], v[72:75], v[174:177], v[132:135]
	v_mfma_f32_16x16x32_bf16 v[132:135], v[146:149], v[178:181], v[132:135]
	v_mfma_f32_16x16x32_bf16 v[120:123], v[64:67], v[182:185], v[120:123]
	v_mfma_f32_16x16x32_bf16 v[120:123], v[68:71], v[194:197], v[120:123]
	v_mfma_f32_16x16x32_bf16 v[116:119], v[72:75], v[182:185], v[116:119]
	v_mfma_f32_16x16x32_bf16 v[116:119], v[146:149], v[194:197], v[116:119]
	v_mfma_f32_16x16x32_bf16 v[104:107], v[64:67], v[198:201], v[104:107]
	v_mfma_f32_16x16x32_bf16 v[104:107], v[68:71], v[202:205], v[104:107]
	v_mfma_f32_16x16x32_bf16 v[100:103], v[72:75], v[198:201], v[100:103]
	v_mfma_f32_16x16x32_bf16 v[100:103], v[146:149], v[202:205], v[100:103]
	v_mfma_f32_16x16x32_bf16 v[88:91], v[64:67], v[206:209], v[88:91]
	v_mfma_f32_16x16x32_bf16 v[88:91], v[68:71], v[210:213], v[88:91]
	v_mfma_f32_16x16x32_bf16 v[84:87], v[72:75], v[206:209], v[84:87]
	v_mfma_f32_16x16x32_bf16 v[84:87], v[146:149], v[210:213], v[84:87]
	s_setprio 0
	s_setprio 1
	v_mfma_f32_16x16x32_bf16 v[128:131], v[150:153], v[174:177], v[128:131]
	v_mfma_f32_16x16x32_bf16 v[128:131], v[154:157], v[178:181], v[128:131]
	v_mfma_f32_16x16x32_bf16 v[124:127], v[158:161], v[174:177], v[124:127]
	v_mfma_f32_16x16x32_bf16 v[124:127], v[170:173], v[178:181], v[124:127]
	v_mfma_f32_16x16x32_bf16 v[112:115], v[150:153], v[182:185], v[112:115]
	v_mfma_f32_16x16x32_bf16 v[112:115], v[154:157], v[194:197], v[112:115]
	v_mfma_f32_16x16x32_bf16 v[108:111], v[158:161], v[182:185], v[108:111]
	v_mfma_f32_16x16x32_bf16 v[108:111], v[170:173], v[194:197], v[108:111]
	v_mfma_f32_16x16x32_bf16 v[96:99], v[150:153], v[198:201], v[96:99]
	v_mfma_f32_16x16x32_bf16 v[96:99], v[154:157], v[202:205], v[96:99]
	v_mfma_f32_16x16x32_bf16 v[92:95], v[158:161], v[198:201], v[92:95]
	v_mfma_f32_16x16x32_bf16 v[92:95], v[170:173], v[202:205], v[92:95]
	v_mfma_f32_16x16x32_bf16 v[80:83], v[150:153], v[206:209], v[80:83]
	v_mfma_f32_16x16x32_bf16 v[80:83], v[154:157], v[210:213], v[80:83]
	v_mfma_f32_16x16x32_bf16 v[76:79], v[158:161], v[206:209], v[76:79]
	v_mfma_f32_16x16x32_bf16 v[76:79], v[170:173], v[210:213], v[76:79]
	s_setprio 0
	s_barrier
; #define PG8_STAGE(bufoff, gbase, voff) do { _Pragma("unroll") for (int _i = 0; _i < 2; ++_i) \
;         __builtin_amdgcn_global_load_lds((const unsigned*)((const char*)(gbase) + (voff)[_i]), (PG8_LAS unsigned*)(lds + (bufoff) + ldsw + _i * 8192), 16, 0, 0); } while (0)
; #define PG8_LDA(dst, b, h) do { _Pragma("unroll") for (int m = 0; m < 4; ++m) _Pragma("unroll") for (int k = 0; k < 2; ++k) dst[m][k] = *(const PG8_LAS bf16x8*)(lds + PG8_SA(b, h) + aoff + m * 2048 + k * 1024); } while (0)
; #define PG8_MMA(ai, bj, At, Bt) do { __builtin_amdgcn_s_setprio(1); _Pragma("unroll") for (int m = 0; m < 4; ++m) _Pragma("unroll") for (int n = 0; n < 2; ++n) _Pragma("unroll") for (int k = 0; k < 2; ++k) \
;         acc[ai][bj][m][n] = __builtin_amdgcn_mfma_f32_16x16x32_bf16(Bt[n][k], At[m][k], acc[ai][bj][m][n], 0, 0, 0); __builtin_amdgcn_s_setprio(0); } while (0)
; #define PG8_WAIT_V(n) asm volatile("s_waitcnt vmcnt(" #n ")" ::: "memory")
; #define PG8_WAIT_L(n) asm volatile("s_waitcnt lgkmcnt(" #n ")" ::: "memory")
; #define PG8_BAR __builtin_amdgcn_s_barrier()
; #define PG8_SCHED __builtin_amdgcn_sched_barrier(0)
; template <class Epi, class Sched, bool ALIGN_EPI = false, bool SP2 = false>
; __device__ __forceinline__ void gemm_phase(PG8_LAS unsigned char* lds, const Gemm g, const Sched& S, const Epi& E) {
;     ...
;             PG8_LDA(At, 1, 1); PG8_STAGE(PG8_SB(1, 0), b3, voffB); PG8_STAGE(PG8_SB(1, 1), b3 + hstep, voffB); PG8_STAGE(PG8_SA(1, 0), a3, voffA);
;             PG8_WAIT_V(8); PG8_WAIT_L(0); PG8_BAR; PG8_MMA(1, 0, At, B0); PG8_MMA(1, 1, At, B1); PG8_BAR; PG8_SCHED;
	s_add_i32 s36, s38, s87
	s_mov_b32 m0, s36
	ds_read_b128 v[174:177], v169 offset:49152
	ds_read_b128 v[178:181], v169 offset:50176
	ds_read_b128 v[182:185], v169 offset:51200
	ds_read_b128 v[194:197], v169 offset:52224
	ds_read_b128 v[198:201], v169 offset:53248
	ds_read_b128 v[202:205], v169 offset:54272
	ds_read_b128 v[206:209], v169 offset:55296
	ds_read_b128 v[210:213], v169 offset:56320
	s_add_u32 s100, s68, 0x80
	s_addc_u32 s101, s69, 0
	global_load_lds_dwordx4 v188, s[100:101]
	s_add_i32 m0, s36, 0x2000
	s_add_u32 s36, s68, 0x80080
	s_addc_u32 s37, s69, 0
	s_add_i32 s38, s39, s87
	global_load_lds_dwordx4 v140, s[100:101]
	s_mov_b32 m0, s38
	s_nop 0
	global_load_lds_dwordx4 v188, s[36:37]
	s_add_i32 m0, s38, 0x2000
	s_nop 0
	global_load_lds_dwordx4 v140, s[36:37]
	s_mov_b32 m0, s81
	s_nop 0
	s_add_u32 s100, s70, 0x80
	s_addc_u32 s101, s71, 0
	global_load_lds_dwordx4 v188, s[100:101]
	s_mov_b32 m0, s80
	s_nop 0
	global_load_lds_dwordx4 v140, s[100:101]
	s_waitcnt vmcnt(8)
	s_waitcnt lgkmcnt(0)
	s_barrier
	s_setprio 1
	s_waitcnt lgkmcnt(0)
	v_mfma_f32_16x16x32_bf16 v[56:59], v[64:67], v[174:177], v[56:59]
	v_mfma_f32_16x16x32_bf16 v[56:59], v[68:71], v[178:181], v[56:59]
	v_mfma_f32_16x16x32_bf16 v[60:63], v[72:75], v[174:177], v[60:63]
	v_mfma_f32_16x16x32_bf16 v[60:63], v[146:149], v[178:181], v[60:63]
	v_mfma_f32_16x16x32_bf16 v[40:43], v[64:67], v[182:185], v[40:43]
	v_mfma_f32_16x16x32_bf16 v[40:43], v[68:71], v[194:197], v[40:43]
	v_mfma_f32_16x16x32_bf16 v[44:47], v[72:75], v[182:185], v[44:47]
	v_mfma_f32_16x16x32_bf16 v[44:47], v[146:149], v[194:197], v[44:47]
	v_mfma_f32_16x16x32_bf16 v[24:27], v[64:67], v[198:201], v[24:27]
	v_mfma_f32_16x16x32_bf16 v[24:27], v[68:71], v[202:205], v[24:27]
	v_mfma_f32_16x16x32_bf16 v[28:31], v[72:75], v[198:201], v[28:31]
	v_mfma_f32_16x16x32_bf16 v[28:31], v[146:149], v[202:205], v[28:31]
	v_mfma_f32_16x16x32_bf16 v[8:11], v[64:67], v[206:209], v[8:11]
	v_mfma_f32_16x16x32_bf16 v[8:11], v[68:71], v[210:213], v[8:11]
	v_mfma_f32_16x16x32_bf16 v[12:15], v[72:75], v[206:209], v[12:15]
	v_mfma_f32_16x16x32_bf16 v[12:15], v[146:149], v[210:213], v[12:15]
	s_setprio 0
	s_setprio 1
	v_mfma_f32_16x16x32_bf16 v[52:55], v[150:153], v[174:177], v[52:55]
	v_mfma_f32_16x16x32_bf16 v[52:55], v[154:157], v[178:181], v[52:55]
	v_mfma_f32_16x16x32_bf16 v[48:51], v[158:161], v[174:177], v[48:51]
	v_mfma_f32_16x16x32_bf16 v[48:51], v[170:173], v[178:181], v[48:51]
	v_mfma_f32_16x16x32_bf16 v[36:39], v[150:153], v[182:185], v[36:39]
	v_mfma_f32_16x16x32_bf16 v[36:39], v[154:157], v[194:197], v[36:39]
	v_mfma_f32_16x16x32_bf16 v[32:35], v[158:161], v[182:185], v[32:35]
	v_mfma_f32_16x16x32_bf16 v[32:35], v[170:173], v[194:197], v[32:35]
	v_mfma_f32_16x16x32_bf16 v[20:23], v[150:153], v[198:201], v[20:23]
	v_mfma_f32_16x16x32_bf16 v[20:23], v[154:157], v[202:205], v[20:23]
	v_mfma_f32_16x16x32_bf16 v[16:19], v[158:161], v[198:201], v[16:19]
	v_mfma_f32_16x16x32_bf16 v[16:19], v[170:173], v[202:205], v[16:19]
	v_mfma_f32_16x16x32_bf16 v[4:7], v[150:153], v[206:209], v[4:7]
	v_mfma_f32_16x16x32_bf16 v[4:7], v[154:157], v[210:213], v[4:7]
	v_mfma_f32_16x16x32_bf16 v[0:3], v[158:161], v[206:209], v[0:3]
	v_mfma_f32_16x16x32_bf16 v[0:3], v[170:173], v[210:213], v[0:3]
	s_setprio 0
	s_barrier
	s_add_i32 s95, s95, 2
	s_add_u32 vcc_lo, vcc_lo, 0x100
	s_addc_u32 vcc_hi, vcc_hi, 0
	s_add_u32 s3, s3, 0x100
	s_addc_u32 s94, s94, 0
	s_cmp_gt_u32 s95, 29

; #define PG8_STAGE(bufoff, gbase, voff) do { _Pragma("unroll") for (int _i = 0; _i < 2; ++_i) \
;         __builtin_amdgcn_global_load_lds((const unsigned*)((const char*)(gbase) + (voff)[_i]), (PG8_LAS unsigned*)(lds + (bufoff) + ldsw + _i * 8192), 16, 0, 0); } while (0)
; #define PG8_LDA(dst, b, h) do { _Pragma("unroll") for (int m = 0; m < 4; ++m) _Pragma("unroll") for (int k = 0; k < 2; ++k) dst[m][k] = *(const PG8_LAS bf16x8*)(lds + PG8_SA(b, h) + aoff + m * 2048 + k * 1024); } while (0)
; #define PG8_LDB(dst, b, h) do { _Pragma("unroll") for (int n = 0; n < 2; ++n) _Pragma("unroll") for (int k = 0; k < 2; ++k) dst[n][k] = *(const PG8_LAS bf16x8*)(lds + PG8_SB(b, h) + boff + n * 2048 + k * 1024); } while (0)
; #define PG8_MMA(ai, bj, At, Bt) do { __builtin_amdgcn_s_setprio(1); _Pragma("unroll") for (int m = 0; m < 4; ++m) _Pragma("unroll") for (int n = 0; n < 2; ++n) _Pragma("unroll") for (int k = 0; k < 2; ++k) \
;         acc[ai][bj][m][n] = __builtin_amdgcn_mfma_f32_16x16x32_bf16(Bt[n][k], At[m][k], acc[ai][bj][m][n], 0, 0, 0); __builtin_amdgcn_s_setprio(0); } while (0)
; #define PG8_WAIT_V(n) asm volatile("s_waitcnt vmcnt(" #n ")" ::: "memory")
; #define PG8_WAIT_L(n) asm volatile("s_waitcnt lgkmcnt(" #n ")" ::: "memory")
; #define PG8_BAR __builtin_amdgcn_s_barrier()
; template <class Epi, class Sched, bool ALIGN_EPI = false, bool SP2 = false>
; __device__ __forceinline__ void gemm_phase(PG8_LAS unsigned char* lds, const Gemm g, const Sched& S, const Epi& E) {
;     ...
;         const bool has_next = S.next(ui + 1, nxt);
;         const char* nA = has_next ? (const char*)g.A + (size_t)nxt.pm * tstep : cA; const char* nB = has_next ? (const char*)g.Bt + (size_t)nxt.pn * tstep : cB;
;         for (int t = 0; t < nt; t += 2) {
;             const bool last = (t == nt - 2);
;             const char* a1 = cA + (size_t)(t + 1) * kstep;
;             const char* a2 = last ? nA : cA + (size_t)(t + 2) * kstep; const char* b2 = last ? nB : cB + (size_t)(t + 2) * kstep;
;             const char* a3 = a2 + kstep; const char* b3 = b2 + kstep;
;             if (last && has_next) S.a_ready(nxt);
;             if constexpr (SP2) {
;             PG8_LDB(B0, 0, 0); PG8_LDB(B1, 0, 1); PG8_SCHED; PG8_LDA(At, 0, 0); PG8_STAGE(PG8_SA(1, 1), a1 + hstep, voffA);
;             PG8_WAIT_V(8); PG8_WAIT_L(0); PG8_BAR; PG8_MMA(0, 0, At, B0); PG8_MMA(0, 1, At, B1); PG8_BAR; PG8_SCHED;
.LBB0_343:
	s_ashr_i32 s57, s56, 31
	s_lshl_b64 s[14:15], s[56:57], 20
	s_add_u32 s44, s34, s14
	s_addc_u32 s45, s35, s15
	s_and_b64 s[14:15], s[4:5], exec
	s_cselect_b32 s7, s45, s9
	s_cselect_b32 s14, s44, s8
	s_ashr_i32 s61, s60, 31
	s_lshl_b64 s[54:55], s[60:61], 20
	s_add_u32 s58, s68, s54
	s_addc_u32 s59, s69, s55
	s_and_b64 s[54:55], s[4:5], exec
	s_cselect_b32 s15, s59, s11
	s_cselect_b32 s54, s58, s10
	s_add_u32 s8, s8, 0x80080
	s_addc_u32 s9, s9, 0
	s_add_u32 s55, s10, 0x100
	s_addc_u32 s3, s11, 0
	s_mov_b32 s57, -2
	s_nop 0
	s_waitcnt vmcnt(16)
	v_add_u32_e32 v218, 0x10000, v167
	s_add_u32 s10, s8, 0xfff80080
	s_addc_u32 s11, s9, -1
	s_add_i32 s36, 0, 0x10000
	s_cmp_eq_u32 s57, 28
	s_cselect_b32 s63, s7, s11
	s_cselect_b32 s62, s14, s10
	s_cselect_b32 s11, s15, s3
	s_cselect_b32 s10, s54, s55
	s_add_i32 s37, 0, 0x14000
	ds_read_b128 v[128:131], v218
	ds_read_b128 v[132:135], v218 offset:1024
	ds_read_b128 v[136:139], v218 offset:2048
	ds_read_b128 v[140:143], v218 offset:3072
	ds_read_b128 v[144:147], v218 offset:16384
	ds_read_b128 v[148:151], v218 offset:17408
	ds_read_b128 v[152:155], v218 offset:18432
	ds_read_b128 v[156:159], v218 offset:19456
	s_add_i32 m0, s53, 0xc000
	ds_read_b128 v[174:177], v204
	ds_read_b128 v[178:181], v204 offset:1024
	ds_read_b128 v[182:185], v204 offset:2048
	ds_read_b128 v[194:197], v204 offset:3072
	ds_read_b128 v[198:201], v204 offset:4096
	ds_read_b128 v[206:209], v204 offset:5120
	ds_read_b128 v[210:213], v204 offset:6144
	ds_read_b128 v[214:217], v204 offset:7168
	global_load_lds_dwordx4 v170, s[8:9]
	s_add_i32 m0, s53, 0xe000
	s_nop 0
	global_load_lds_dwordx4 v172, s[8:9]
	s_waitcnt vmcnt(24)
	s_waitcnt lgkmcnt(0)
	s_barrier
	s_setprio 1
	s_waitcnt lgkmcnt(0)
	v_mfma_f32_16x16x32_bf16 v[124:127], v[128:131], v[174:177], 0
	v_mfma_f32_16x16x32_bf16 v[124:127], v[132:135], v[178:181], v[124:127]
	v_mfma_f32_16x16x32_bf16 v[120:123], v[136:139], v[174:177], 0
	v_mfma_f32_16x16x32_bf16 v[120:123], v[140:143], v[178:181], v[120:123]
	v_mfma_f32_16x16x32_bf16 v[108:111], v[128:131], v[182:185], 0
	v_mfma_f32_16x16x32_bf16 v[108:111], v[132:135], v[194:197], v[108:111]
	v_mfma_f32_16x16x32_bf16 v[104:107], v[136:139], v[182:185], 0
	v_mfma_f32_16x16x32_bf16 v[104:107], v[140:143], v[194:197], v[104:107]
	v_mfma_f32_16x16x32_bf16 v[92:95], v[128:131], v[198:201], 0
	v_mfma_f32_16x16x32_bf16 v[92:95], v[132:135], v[206:209], v[92:95]
	v_mfma_f32_16x16x32_bf16 v[88:91], v[136:139], v[198:201], 0
	v_mfma_f32_16x16x32_bf16 v[88:91], v[140:143], v[206:209], v[88:91]
	v_mfma_f32_16x16x32_bf16 v[76:79], v[128:131], v[210:213], 0
	v_mfma_f32_16x16x32_bf16 v[76:79], v[132:135], v[214:217], v[76:79]
	v_mfma_f32_16x16x32_bf16 v[72:75], v[136:139], v[210:213], 0
	v_mfma_f32_16x16x32_bf16 v[72:75], v[140:143], v[214:217], v[72:75]
	s_setprio 0
	s_setprio 1
	v_mfma_f32_16x16x32_bf16 v[116:119], v[144:147], v[174:177], 0
	v_mfma_f32_16x16x32_bf16 v[116:119], v[148:151], v[178:181], v[116:119]
	v_mfma_f32_16x16x32_bf16 v[112:115], v[152:155], v[174:177], 0
	v_mfma_f32_16x16x32_bf16 v[112:115], v[156:159], v[178:181], v[112:115]
	v_mfma_f32_16x16x32_bf16 v[100:103], v[144:147], v[182:185], 0
	v_mfma_f32_16x16x32_bf16 v[100:103], v[148:151], v[194:197], v[100:103]
	v_mfma_f32_16x16x32_bf16 v[96:99], v[152:155], v[182:185], 0
	v_mfma_f32_16x16x32_bf16 v[96:99], v[156:159], v[194:197], v[96:99]
	v_mfma_f32_16x16x32_bf16 v[84:87], v[144:147], v[198:201], 0
	v_mfma_f32_16x16x32_bf16 v[84:87], v[148:151], v[206:209], v[84:87]
	v_mfma_f32_16x16x32_bf16 v[80:83], v[152:155], v[198:201], 0
	v_mfma_f32_16x16x32_bf16 v[80:83], v[156:159], v[206:209], v[80:83]
	v_mfma_f32_16x16x32_bf16 v[68:71], v[144:147], v[210:213], 0
	v_mfma_f32_16x16x32_bf16 v[68:71], v[148:151], v[214:217], v[68:71]
	v_mfma_f32_16x16x32_bf16 v[64:67], v[152:155], v[210:213], 0
	v_mfma_f32_16x16x32_bf16 v[64:67], v[156:159], v[214:217], v[64:67]
	s_setprio 0
	s_barrier
	s_add_i32 s36, s36, s70
	s_mov_b32 m0, s36
	ds_read_b128 v[174:177], v204 offset:16384
	ds_read_b128 v[178:181], v204 offset:17408
	ds_read_b128 v[182:185], v204 offset:18432
	ds_read_b128 v[194:197], v204 offset:19456
	ds_read_b128 v[198:201], v204 offset:20480
	ds_read_b128 v[206:209], v204 offset:21504
	ds_read_b128 v[210:213], v204 offset:22528
	ds_read_b128 v[214:217], v204 offset:23552
	global_load_lds_dwordx4 v160, s[10:11]
	s_add_i32 m0, s36, 0x2000
	s_add_u32 s64, s10, 0x80000
	s_addc_u32 s65, s11, 0
	s_add_i32 s36, s37, s70
	global_load_lds_dwordx4 v162, s[10:11]
	s_mov_b32 m0, s36
	s_nop 0
	global_load_lds_dwordx4 v160, s[64:65]
	s_add_i32 m0, s36, 0x2000
	s_nop 0
	global_load_lds_dwordx4 v162, s[64:65]
	s_mov_b32 m0, s53
	s_nop 0
	global_load_lds_dwordx4 v160, s[62:63]
	s_mov_b32 m0, s71
	s_nop 0
	global_load_lds_dwordx4 v162, s[62:63]
	s_waitcnt vmcnt(24)
	s_waitcnt lgkmcnt(0)
	s_barrier
; #define PG8_STAGE(bufoff, gbase, voff) do { _Pragma("unroll") for (int _i = 0; _i < 2; ++_i) \
;         __builtin_amdgcn_global_load_lds((const unsigned*)((const char*)(gbase) + (voff)[_i]), (PG8_LAS unsigned*)(lds + (bufoff) + ldsw + _i * 8192), 16, 0, 0); } while (0)
; #define PG8_LDA(dst, b, h) do { _Pragma("unroll") for (int m = 0; m < 4; ++m) _Pragma("unroll") for (int k = 0; k < 2; ++k) dst[m][k] = *(const PG8_LAS bf16x8*)(lds + PG8_SA(b, h) + aoff + m * 2048 + k * 1024); } while (0)
; #define PG8_LDB(dst, b, h) do { _Pragma("unroll") for (int n = 0; n < 2; ++n) _Pragma("unroll") for (int k = 0; k < 2; ++k) dst[n][k] = *(const PG8_LAS bf16x8*)(lds + PG8_SB(b, h) + boff + n * 2048 + k * 1024); } while (0)
; #define PG8_MMA(ai, bj, At, Bt) do { __builtin_amdgcn_s_setprio(1); _Pragma("unroll") for (int m = 0; m < 4; ++m) _Pragma("unroll") for (int n = 0; n < 2; ++n) _Pragma("unroll") for (int k = 0; k < 2; ++k) \
;         acc[ai][bj][m][n] = __builtin_amdgcn_mfma_f32_16x16x32_bf16(Bt[n][k], At[m][k], acc[ai][bj][m][n], 0, 0, 0); __builtin_amdgcn_s_setprio(0); } while (0)
; #define PG8_WAIT_V(n) asm volatile("s_waitcnt vmcnt(" #n ")" ::: "memory")
; #define PG8_WAIT_L(n) asm volatile("s_waitcnt lgkmcnt(" #n ")" ::: "memory")
; #define PG8_BAR __builtin_amdgcn_s_barrier()
; #define PG8_SCHED __builtin_amdgcn_sched_barrier(0)
; template <class Epi, class Sched, bool ALIGN_EPI = false, bool SP2 = false>
; __device__ __forceinline__ void gemm_phase(PG8_LAS unsigned char* lds, const Gemm g, const Sched& S, const Epi& E) {
;     ...
;             PG8_WAIT_V(8); PG8_WAIT_L(0); PG8_BAR; PG8_MMA(0, 0, At, B0); PG8_MMA(0, 1, At, B1); PG8_BAR; PG8_SCHED;
;             PG8_LDA(At, 0, 1); PG8_STAGE(PG8_SB(0, 0), b2, voffB); PG8_STAGE(PG8_SB(0, 1), b2 + hstep, voffB); PG8_STAGE(PG8_SA(0, 0), a2, voffA);
;             PG8_WAIT_V(8); PG8_WAIT_L(0); PG8_BAR; PG8_MMA(1, 0, At, B0); PG8_MMA(1, 1, At, B1); PG8_BAR; PG8_SCHED;
;             PG8_LDB(B0, 1, 0); PG8_LDB(B1, 1, 1); PG8_SCHED; PG8_LDA(At, 1, 0); PG8_STAGE(PG8_SA(0, 1), a2 + hstep, voffA);
;             PG8_WAIT_V(8); PG8_WAIT_L(0); PG8_BAR; PG8_MMA(0, 0, At, B0); PG8_MMA(0, 1, At, B1); PG8_BAR; PG8_SCHED;
	s_setprio 1
	s_waitcnt lgkmcnt(0)
	v_mfma_f32_16x16x32_bf16 v[60:63], v[128:131], v[174:177], 0
	v_mfma_f32_16x16x32_bf16 v[60:63], v[132:135], v[178:181], v[60:63]
	v_mfma_f32_16x16x32_bf16 v[56:59], v[136:139], v[174:177], 0
	v_mfma_f32_16x16x32_bf16 v[56:59], v[140:143], v[178:181], v[56:59]
	v_mfma_f32_16x16x32_bf16 v[44:47], v[128:131], v[182:185], 0
	v_mfma_f32_16x16x32_bf16 v[44:47], v[132:135], v[194:197], v[44:47]
	v_mfma_f32_16x16x32_bf16 v[40:43], v[136:139], v[182:185], 0
	v_mfma_f32_16x16x32_bf16 v[40:43], v[140:143], v[194:197], v[40:43]
	v_mfma_f32_16x16x32_bf16 v[28:31], v[128:131], v[198:201], 0
	v_mfma_f32_16x16x32_bf16 v[28:31], v[132:135], v[206:209], v[28:31]
	v_mfma_f32_16x16x32_bf16 v[24:27], v[136:139], v[198:201], 0
	v_mfma_f32_16x16x32_bf16 v[24:27], v[140:143], v[206:209], v[24:27]
	v_mfma_f32_16x16x32_bf16 v[12:15], v[128:131], v[210:213], 0
	v_mfma_f32_16x16x32_bf16 v[12:15], v[132:135], v[214:217], v[12:15]
	v_mfma_f32_16x16x32_bf16 v[8:11], v[136:139], v[210:213], 0
	v_mfma_f32_16x16x32_bf16 v[8:11], v[140:143], v[214:217], v[8:11]
	s_setprio 0
	s_setprio 1
	v_mfma_f32_16x16x32_bf16 v[52:55], v[144:147], v[174:177], 0
	v_mfma_f32_16x16x32_bf16 v[52:55], v[148:151], v[178:181], v[52:55]
	v_mfma_f32_16x16x32_bf16 v[48:51], v[152:155], v[174:177], 0
	v_mfma_f32_16x16x32_bf16 v[48:51], v[156:159], v[178:181], v[48:51]
	v_mfma_f32_16x16x32_bf16 v[36:39], v[144:147], v[182:185], 0
	v_mfma_f32_16x16x32_bf16 v[36:39], v[148:151], v[194:197], v[36:39]
	v_mfma_f32_16x16x32_bf16 v[32:35], v[152:155], v[182:185], 0
	v_mfma_f32_16x16x32_bf16 v[32:35], v[156:159], v[194:197], v[32:35]
	v_mfma_f32_16x16x32_bf16 v[20:23], v[144:147], v[198:201], 0
	v_mfma_f32_16x16x32_bf16 v[20:23], v[148:151], v[206:209], v[20:23]
	v_mfma_f32_16x16x32_bf16 v[16:19], v[152:155], v[198:201], 0
	v_mfma_f32_16x16x32_bf16 v[16:19], v[156:159], v[206:209], v[16:19]
	v_mfma_f32_16x16x32_bf16 v[4:7], v[144:147], v[210:213], 0
	v_mfma_f32_16x16x32_bf16 v[4:7], v[148:151], v[214:217], v[4:7]
	v_mfma_f32_16x16x32_bf16 v[0:3], v[152:155], v[210:213], 0
	v_mfma_f32_16x16x32_bf16 v[0:3], v[156:159], v[214:217], v[0:3]
	s_setprio 0
	s_barrier
	s_add_i32 s36, 0, 0x18000
	s_add_i32 s37, 0, 0x1c000
	ds_read_b128 v[128:131], v218 offset:32768
	ds_read_b128 v[132:135], v218 offset:33792
	ds_read_b128 v[136:139], v218 offset:34816
	ds_read_b128 v[140:143], v218 offset:35840
	ds_read_b128 v[144:147], v218 offset:49152
	ds_read_b128 v[148:151], v218 offset:50176
	ds_read_b128 v[152:155], v218 offset:51200
	ds_read_b128 v[156:159], v218 offset:52224
	s_add_u32 s62, s62, 0x80000
	s_addc_u32 s63, s63, 0
	s_mov_b32 m0, s72
	ds_read_b128 v[174:177], v204 offset:32768
	ds_read_b128 v[178:181], v204 offset:33792
	ds_read_b128 v[182:185], v204 offset:34816
	ds_read_b128 v[194:197], v204 offset:35840
	ds_read_b128 v[198:201], v204 offset:36864
	ds_read_b128 v[206:209], v204 offset:37888
	ds_read_b128 v[210:213], v204 offset:38912
	ds_read_b128 v[214:217], v204 offset:39936
	global_load_lds_dwordx4 v160, s[62:63]
	s_mov_b32 m0, s73
	s_nop 0
	global_load_lds_dwordx4 v162, s[62:63]
	s_waitcnt vmcnt(8)
	s_waitcnt lgkmcnt(0)
	s_barrier
	s_setprio 1
	s_waitcnt lgkmcnt(0)
	v_mfma_f32_16x16x32_bf16 v[124:127], v[128:131], v[174:177], v[124:127]
	v_mfma_f32_16x16x32_bf16 v[124:127], v[132:135], v[178:181], v[124:127]
	v_mfma_f32_16x16x32_bf16 v[120:123], v[136:139], v[174:177], v[120:123]
	v_mfma_f32_16x16x32_bf16 v[120:123], v[140:143], v[178:181], v[120:123]
	v_mfma_f32_16x16x32_bf16 v[108:111], v[128:131], v[182:185], v[108:111]
	v_mfma_f32_16x16x32_bf16 v[108:111], v[132:135], v[194:197], v[108:111]
	v_mfma_f32_16x16x32_bf16 v[104:107], v[136:139], v[182:185], v[104:107]
	v_mfma_f32_16x16x32_bf16 v[104:107], v[140:143], v[194:197], v[104:107]
	v_mfma_f32_16x16x32_bf16 v[92:95], v[128:131], v[198:201], v[92:95]
	v_mfma_f32_16x16x32_bf16 v[92:95], v[132:135], v[206:209], v[92:95]
	v_mfma_f32_16x16x32_bf16 v[88:91], v[136:139], v[198:201], v[88:91]
	v_mfma_f32_16x16x32_bf16 v[88:91], v[140:143], v[206:209], v[88:91]
	v_mfma_f32_16x16x32_bf16 v[76:79], v[128:131], v[210:213], v[76:79]
	v_mfma_f32_16x16x32_bf16 v[76:79], v[132:135], v[214:217], v[76:79]
	v_mfma_f32_16x16x32_bf16 v[72:75], v[136:139], v[210:213], v[72:75]
	v_mfma_f32_16x16x32_bf16 v[72:75], v[140:143], v[214:217], v[72:75]
	s_setprio 0
	s_setprio 1
	v_mfma_f32_16x16x32_bf16 v[116:119], v[144:147], v[174:177], v[116:119]
	v_mfma_f32_16x16x32_bf16 v[116:119], v[148:151], v[178:181], v[116:119]
	v_mfma_f32_16x16x32_bf16 v[112:115], v[152:155], v[174:177], v[112:115]
	v_mfma_f32_16x16x32_bf16 v[112:115], v[156:159], v[178:181], v[112:115]
	v_mfma_f32_16x16x32_bf16 v[100:103], v[144:147], v[182:185], v[100:103]
	v_mfma_f32_16x16x32_bf16 v[100:103], v[148:151], v[194:197], v[100:103]
	v_mfma_f32_16x16x32_bf16 v[96:99], v[152:155], v[182:185], v[96:99]
	v_mfma_f32_16x16x32_bf16 v[96:99], v[156:159], v[194:197], v[96:99]
	v_mfma_f32_16x16x32_bf16 v[84:87], v[144:147], v[198:201], v[84:87]
	v_mfma_f32_16x16x32_bf16 v[84:87], v[148:151], v[206:209], v[84:87]
	v_mfma_f32_16x16x32_bf16 v[80:83], v[152:155], v[198:201], v[80:83]
	v_mfma_f32_16x16x32_bf16 v[80:83], v[156:159], v[206:209], v[80:83]
	v_mfma_f32_16x16x32_bf16 v[68:71], v[144:147], v[210:213], v[68:71]
	v_mfma_f32_16x16x32_bf16 v[68:71], v[148:151], v[214:217], v[68:71]
	v_mfma_f32_16x16x32_bf16 v[64:67], v[152:155], v[210:213], v[64:67]
	v_mfma_f32_16x16x32_bf16 v[64:67], v[156:159], v[214:217], v[64:67]
	s_setprio 0
	s_barrier
; #define PG8_STAGE(bufoff, gbase, voff) do { _Pragma("unroll") for (int _i = 0; _i < 2; ++_i) \
;         __builtin_amdgcn_global_load_lds((const unsigned*)((const char*)(gbase) + (voff)[_i]), (PG8_LAS unsigned*)(lds + (bufoff) + ldsw + _i * 8192), 16, 0, 0); } while (0)
; #define PG8_LDA(dst, b, h) do { _Pragma("unroll") for (int m = 0; m < 4; ++m) _Pragma("unroll") for (int k = 0; k < 2; ++k) dst[m][k] = *(const PG8_LAS bf16x8*)(lds + PG8_SA(b, h) + aoff + m * 2048 + k * 1024); } while (0)
; #define PG8_MMA(ai, bj, At, Bt) do { __builtin_amdgcn_s_setprio(1); _Pragma("unroll") for (int m = 0; m < 4; ++m) _Pragma("unroll") for (int n = 0; n < 2; ++n) _Pragma("unroll") for (int k = 0; k < 2; ++k) \
;         acc[ai][bj][m][n] = __builtin_amdgcn_mfma_f32_16x16x32_bf16(Bt[n][k], At[m][k], acc[ai][bj][m][n], 0, 0, 0); __builtin_amdgcn_s_setprio(0); } while (0)
; #define PG8_WAIT_V(n) asm volatile("s_waitcnt vmcnt(" #n ")" ::: "memory")
; #define PG8_WAIT_L(n) asm volatile("s_waitcnt lgkmcnt(" #n ")" ::: "memory")
; #define PG8_BAR __builtin_amdgcn_s_barrier()
; #define PG8_SCHED __builtin_amdgcn_sched_barrier(0)
; template <class Epi, class Sched, bool ALIGN_EPI = false, bool SP2 = false>
; __device__ __forceinline__ void gemm_phase(PG8_LAS unsigned char* lds, const Gemm g, const Sched& S, const Epi& E) {
;     ...
;             PG8_LDA(At, 1, 1); PG8_STAGE(PG8_SB(1, 0), b3, voffB); PG8_STAGE(PG8_SB(1, 1), b3 + hstep, voffB); PG8_STAGE(PG8_SA(1, 0), a3, voffA);
;             PG8_WAIT_V(8); PG8_WAIT_L(0); PG8_BAR; PG8_MMA(1, 0, At, B0); PG8_MMA(1, 1, At, B1); PG8_BAR; PG8_SCHED;
	s_add_i32 s36, s36, s70
	s_mov_b32 m0, s36
	ds_read_b128 v[174:177], v204 offset:49152
	ds_read_b128 v[178:181], v204 offset:50176
	ds_read_b128 v[182:185], v204 offset:51200
	ds_read_b128 v[194:197], v204 offset:52224
	ds_read_b128 v[198:201], v204 offset:53248
	ds_read_b128 v[206:209], v204 offset:54272
	ds_read_b128 v[210:213], v204 offset:55296
	ds_read_b128 v[214:217], v204 offset:56320
	s_add_u32 s100, s10, 0x80
	s_addc_u32 s101, s11, 0
	global_load_lds_dwordx4 v160, s[100:101]
	s_add_i32 m0, s36, 0x2000
	s_add_u32 s10, s10, 0x80080
	s_addc_u32 s11, s11, 0
	s_add_i32 s36, s37, s70
	s_add_u32 s100, s10, 0xfff80000
	s_addc_u32 s101, s11, -1
	global_load_lds_dwordx4 v162, s[100:101]
	s_mov_b32 m0, s36
	s_nop 0
	global_load_lds_dwordx4 v160, s[10:11]
	s_add_i32 m0, s36, 0x2000
	s_nop 0
	global_load_lds_dwordx4 v162, s[10:11]
	s_mov_b32 m0, s76
	s_nop 0
	s_add_u32 s100, s62, 0xfff80080
	s_addc_u32 s101, s63, -1
	global_load_lds_dwordx4 v160, s[100:101]
	s_mov_b32 m0, s77
	s_nop 0
	global_load_lds_dwordx4 v162, s[100:101]
	s_waitcnt vmcnt(8)
	s_waitcnt lgkmcnt(0)
	s_barrier
	s_setprio 1
	s_waitcnt lgkmcnt(0)
	v_mfma_f32_16x16x32_bf16 v[60:63], v[128:131], v[174:177], v[60:63]
	v_mfma_f32_16x16x32_bf16 v[60:63], v[132:135], v[178:181], v[60:63]
	v_mfma_f32_16x16x32_bf16 v[56:59], v[136:139], v[174:177], v[56:59]
	v_mfma_f32_16x16x32_bf16 v[56:59], v[140:143], v[178:181], v[56:59]
	v_mfma_f32_16x16x32_bf16 v[44:47], v[128:131], v[182:185], v[44:47]
	v_mfma_f32_16x16x32_bf16 v[44:47], v[132:135], v[194:197], v[44:47]
	v_mfma_f32_16x16x32_bf16 v[40:43], v[136:139], v[182:185], v[40:43]
	v_mfma_f32_16x16x32_bf16 v[40:43], v[140:143], v[194:197], v[40:43]
	v_mfma_f32_16x16x32_bf16 v[28:31], v[128:131], v[198:201], v[28:31]
	v_mfma_f32_16x16x32_bf16 v[28:31], v[132:135], v[206:209], v[28:31]
	v_mfma_f32_16x16x32_bf16 v[24:27], v[136:139], v[198:201], v[24:27]
	v_mfma_f32_16x16x32_bf16 v[24:27], v[140:143], v[206:209], v[24:27]
	v_mfma_f32_16x16x32_bf16 v[12:15], v[128:131], v[210:213], v[12:15]
	v_mfma_f32_16x16x32_bf16 v[12:15], v[132:135], v[214:217], v[12:15]
	v_mfma_f32_16x16x32_bf16 v[8:11], v[136:139], v[210:213], v[8:11]
	v_mfma_f32_16x16x32_bf16 v[8:11], v[140:143], v[214:217], v[8:11]
	s_setprio 0
	s_setprio 1
	v_mfma_f32_16x16x32_bf16 v[52:55], v[144:147], v[174:177], v[52:55]
	v_mfma_f32_16x16x32_bf16 v[52:55], v[148:151], v[178:181], v[52:55]
	v_mfma_f32_16x16x32_bf16 v[48:51], v[152:155], v[174:177], v[48:51]
	v_mfma_f32_16x16x32_bf16 v[48:51], v[156:159], v[178:181], v[48:51]
	v_mfma_f32_16x16x32_bf16 v[36:39], v[144:147], v[182:185], v[36:39]
	v_mfma_f32_16x16x32_bf16 v[36:39], v[148:151], v[194:197], v[36:39]
	v_mfma_f32_16x16x32_bf16 v[32:35], v[152:155], v[182:185], v[32:35]
	v_mfma_f32_16x16x32_bf16 v[32:35], v[156:159], v[194:197], v[32:35]
	v_mfma_f32_16x16x32_bf16 v[20:23], v[144:147], v[198:201], v[20:23]
	v_mfma_f32_16x16x32_bf16 v[20:23], v[148:151], v[206:209], v[20:23]
	v_mfma_f32_16x16x32_bf16 v[16:19], v[152:155], v[198:201], v[16:19]
	v_mfma_f32_16x16x32_bf16 v[16:19], v[156:159], v[206:209], v[16:19]
	v_mfma_f32_16x16x32_bf16 v[4:7], v[144:147], v[210:213], v[4:7]
	v_mfma_f32_16x16x32_bf16 v[4:7], v[148:151], v[214:217], v[4:7]
	v_mfma_f32_16x16x32_bf16 v[0:3], v[152:155], v[210:213], v[0:3]
	v_mfma_f32_16x16x32_bf16 v[0:3], v[156:159], v[214:217], v[0:3]
	s_setprio 0
	s_barrier
	s_add_i32 s57, s57, 2
	s_add_u32 s8, s8, 0x100
	s_addc_u32 s9, s9, 0
	s_add_u32 s55, s55, 0x100
	s_addc_u32 s3, s3, 0
	s_cmp_gt_u32 s57, 29
